# mixer weight conversion loop (mid-rowwise phase) given the same deferred-copy prefetch fix
# baseline (speedup 1.0000x reference)
; __device__ __forceinline__ unsigned pk2(float lo, float hi) { unsigned r; asm("v_cvt_pk_bf16_f32 %0, %1, %2" : "=v"(r) : "v"(lo), "v"(hi)); return r; }
; __device__ __forceinline__ void cvt_store(const CvtJob& jb, int tid, const float* scr) {
;     const int nkt = jb.K / 64, nb = jb.tile / nkt, kb = jb.tile % nkt, n0 = nb * 64, k0 = kb * 64;
;     const int nl = tid >> 3, kc = tid & 7; const float* sp = scr + (kc * 8) * 65 + nl;
;     u32x4 o; o.x = pk2(sp[0], sp[65]); o.y = pk2(sp[2 * 65], sp[3 * 65]); o.z = pk2(sp[4 * 65], sp[5 * 65]); o.w = pk2(sp[6 * 65], sp[7 * 65]);
;     *(u32x4*)(jb.Wt + (size_t)(n0 + nl) * jb.ldw + k0 + kc * 8) = o;
; __device__ __forceinline__ void convert_layer_weights(const Params& p, uchar* sm, int i, bool mixer, bool ffn) {
;     ...
;     f32x4 cur[2], nxt[2];
;     int it = bid;
;     if (it < n_all) cvt_load(job(it), tid, cur);
;     for (; it < n_all; it += gridDim.x) {
;         const CvtJob jb = job(it);
;         cvt_to_lds(tid, cur, scr);
;         if (it + (int)gridDim.x < n_all) cvt_load(job(it + gridDim.x), tid, nxt);
;         __syncthreads();
;         cvt_store(jb, tid, scr);
;         __syncthreads();
;         cur[0] = nxt[0]; cur[1] = nxt[1];
.LBB0_941:
	s_bitcmp1_b32 s22, 0
	s_waitcnt vmcnt(0)
	v_lshlrev_b32_e32 v2, 3, v8
	s_cselect_b64 s[0:1], -1, 0
	v_ashrrev_i32_e32 v23, 3, v8
	v_and_b32_e32 v4, 56, v2
	s_xor_b64 s[14:15], s[0:1], -1
	s_movk_i32 s0, 0x104
	v_mul_u32_u24_e32 v2, 0x104, v4
	v_lshlrev_b32_e32 v6, 2, v23
	v_lshl_add_u32 v3, v1, 2, 0
	v_mul_lo_u32 v5, v14, s0
	v_add3_u32 v24, 0, v2, v6
	s_sub_i32 s36, 0, s30
	s_sub_i32 s37, s94, s31
	v_add_u32_e32 v25, v3, v5
	v_lshlrev_b32_e32 v16, 1, v4
	s_waitcnt vmcnt(0)
	v_mov_b32_e32 v2, v10
	v_mov_b32_e32 v3, v11
	v_mov_b32_e32 v4, v12
	v_mov_b32_e32 v5, v13
	v_mov_b32_e32 v6, v20
	v_mov_b32_e32 v7, v21
	v_mov_b32_e32 v8, v18
	v_mov_b32_e32 v9, v19
	s_branch .LBB0_943
.LBB0_942:
	s_abs_i32 s22, s40
	v_cvt_f32_u32_e32 v10, s22
	s_sub_i32 s23, 0, s22
	s_abs_i32 s1, s38
	s_xor_b32 s0, s38, s40
	v_rcp_iflag_f32_e32 v10, v10
	s_ashr_i32 s0, s0, 31
	s_waitcnt lgkmcnt(0)
	s_barrier
	v_mul_f32_e32 v10, 0x4f7ffffe, v10
	v_cvt_u32_f32_e32 v10, v10
	ds_read2_b32 v[12:13], v24 offset0:130 offset1:195
	v_add_u32_e32 v17, 0x400, v24
	v_readfirstlane_b32 s24, v10
	s_mul_i32 s23, s23, s24
	s_mul_hi_u32 s23, s24, s23
	s_add_i32 s24, s24, s23
	s_mul_hi_u32 s23, s1, s24
	s_mul_i32 s24, s23, s22
	s_sub_i32 s1, s1, s24
	s_add_i32 s24, s23, 1
	s_sub_i32 s25, s1, s22
	s_cmp_ge_u32 s1, s22
	s_cselect_b32 s23, s24, s23
	s_cselect_b32 s1, s25, s1
	s_add_i32 s24, s23, 1
	s_cmp_ge_u32 s1, s22
	s_cselect_b32 s1, s24, s23
	s_xor_b32 s1, s1, s0
	s_sub_i32 s1, s1, s0
	ds_read2_b32 v[10:11], v24 offset1:65
	s_waitcnt lgkmcnt(0)
	v_cvt_pk_bf16_f32 v10, v10, v11
	v_cvt_pk_bf16_f32 v11, v12, v13
	ds_read2_b32 v[12:13], v17 offset0:4 offset1:69
	ds_read2_b32 v[18:19], v17 offset0:134 offset1:199
	v_lshl_add_u32 v17, s1, 6, v23
	s_mul_i32 s0, s1, s40
	s_waitcnt lgkmcnt(1)
	v_cvt_pk_bf16_f32 v12, v12, v13
	s_waitcnt lgkmcnt(0)
	v_cvt_pk_bf16_f32 v13, v18, v19
	v_ashrrev_i32_e32 v18, 31, v17
	s_sub_i32 s0, s38, s0
	v_mul_lo_u32 v20, s18, v18
	v_mul_lo_u32 v21, s19, v17
	v_mad_u64_u32 v[18:19], s[18:19], s18, v17, 0
	s_lshl_b32 s0, s0, 6
	v_add3_u32 v19, v19, v20, v21
	v_lshl_add_u64 v[18:19], v[18:19], 1, s[16:17]
	s_ashr_i32 s1, s0, 31
	v_lshl_add_u64 v[18:19], s[0:1], 1, v[18:19]
	v_mov_b32_e32 v17, v0
	v_lshl_add_u64 v[18:19], v[18:19], 0, v[16:17]
	global_store_dwordx4 v[18:19], v[10:13], off
	s_andn2_b64 vcc, exec, s[20:21]
	s_mov_b32 s28, s39
	s_barrier
	s_cbranch_vccz .LBB0_971

; __device__ __forceinline__ void cvt_to_lds(int tid, const f32x4 (&v)[2], float* scr) {
;     const int n4 = (tid & 15) * 4, kk0 = tid >> 4;
; #pragma unroll
;     for (int i = 0; i < 2; ++i) { float* d = scr + (kk0 + 32 * i) * 65 + n4; d[0] = v[i][0]; d[1] = v[i][1]; d[2] = v[i][2]; d[3] = v[i][3]; }
; }
; __device__ __forceinline__ void convert_layer_weights(const Params& p, uchar* sm, int i, bool mixer, bool ffn) {
;     ...
;     for (; it < n_all; it += gridDim.x) {
;         const CvtJob jb = job(it);
;         cvt_to_lds(tid, cur, scr);
;         if (it + (int)gridDim.x < n_all) cvt_load(job(it + gridDim.x), tid, nxt);
.LBB0_951:
	s_waitcnt vmcnt(0)
	v_mov_b32_e32 v10, v2
	v_mov_b32_e32 v11, v3
	v_mov_b32_e32 v12, v4
	v_mov_b32_e32 v13, v5
	v_mov_b32_e32 v20, v6
	v_mov_b32_e32 v21, v7
	v_mov_b32_e32 v18, v8
	v_mov_b32_e32 v19, v9
	s_add_i32 s39, s28, s94
	s_cmp_ge_i32 s39, s30
	ds_write2_b32 v25, v10, v11 offset1:1
	ds_write2_b32 v25, v12, v13 offset0:2 offset1:3
	v_add_u32_e32 v10, 0x2080, v25
	s_cselect_b64 s[20:21], -1, 0
	ds_write2_b32 v10, v20, v21 offset1:1
	v_add_u32_e32 v10, 0x2088, v25
	s_and_b64 vcc, exec, s[20:21]
	ds_write2_b32 v10, v18, v19 offset1:1
	s_cbranch_vccnz .LBB0_942
	s_cmp_ge_i32 s39, s31
	s_cselect_b64 s[0:1], -1, 0
	v_cndmask_b32_e64 v2, 0, 1, s[0:1]
	s_mov_b64 s[26:27], -1
	s_andn2_b64 vcc, exec, s[14:15]
	v_cmp_ne_u32_e64 s[0:1], 1, v2
	s_cbranch_vccnz .LBB0_955
	s_and_b64 vcc, exec, s[0:1]
	s_cbranch_vccnz .LBB0_958
	s_sub_i32 s29, s39, s31
	s_movk_i32 s41, 0x400
	s_mov_b64 s[24:25], 0
	s_mov_b64 s[22:23], s[10:11]
	s_mov_b64 s[26:27], 0
